# v43 with sc1 (L2-bypassing) dummy prefetch loads in the P6/P9 K-loops: fill the memory-side cache without displacing the GEMM's L2 working set
# speedup vs baseline: 1.0151x; 1.0151x over previous
.LBB0_872:
	ds_read_b128 v[16:19], v191
	ds_read_b128 v[20:23], v191 offset:1024
	ds_read_b128 v[24:27], v191 offset:2048
	ds_read_b128 v[28:31], v191 offset:3072
	ds_read_b128 v[0:3], v192
	ds_read_b128 v[4:7], v192 offset:1024
	ds_read_b128 v[8:11], v192 offset:2048
	ds_read_b128 v[12:15], v192 offset:3072
	s_add_u32 s58, s56, 0xfffc0080
	s_addc_u32 s59, s57, -1
	s_cmp_eq_u32 s72, 12
	s_cselect_b32 s61, s45, s59
	s_cselect_b32 s60, s53, s58
	s_cselect_b32 s59, s43, s71
	s_cselect_b32 s58, s69, s70
	v_lshl_add_u64 v[218:219], s[56:57], 0, v[168:169]
	s_add_i32 m0, s18, 0xc000
	ds_read_b128 v[176:179], v193
	ds_read_b128 v[180:183], v193 offset:1024
	ds_read_b128 v[194:197], v193 offset:2048
	ds_read_b128 v[198:201], v193 offset:3072
	ds_read_b128 v[202:205], v193 offset:4096
	ds_read_b128 v[206:209], v193 offset:5120
	ds_read_b128 v[210:213], v193 offset:6144
	ds_read_b128 v[214:217], v193 offset:7168
	global_load_lds_dwordx4 v[218:219], off
	v_lshl_add_u64 v[218:219], s[56:57], 0, v[170:171]
	s_add_i32 m0, s18, 0xe000
	s_nop 0
	global_load_lds_dwordx4 v[218:219], off
	s_waitcnt vmcnt(8)
	s_add_u32 s79, s72, 2
	s_bitcmp1_b32 s79, 3
	s_cselect_b64 s[84:85], s[82:83], s[80:81]
	s_bfe_u32 s86, s79, 0x10002
	s_lshl_b32 s86, s86, 24
	s_bfe_u32 s87, s79, 0x10001
	s_lshl_b32 s87, s87, 12
	s_add_u32 s86, s86, s87
	v_add_u32_e32 v229, s86, v228
	global_load_dword v230, v229, s[84:85] sc1
	s_nop 0
	s_waitcnt lgkmcnt(0)
	s_barrier
	s_setprio 1
	s_waitcnt lgkmcnt(0)
	v_mfma_scale_f32_16x16x128_f8f6f4 v[156:159], v[16:23], v[176:183], v[156:159], v186, v187 op_sel_hi:[0,0,0]
	v_mfma_scale_f32_16x16x128_f8f6f4 v[152:155], v[24:31], v[176:183], v[152:155], v186, v187 op_sel_hi:[0,0,0]
	v_mfma_scale_f32_16x16x128_f8f6f4 v[140:143], v[16:23], v[194:201], v[140:143], v186, v187 op_sel_hi:[0,0,0]
	v_mfma_scale_f32_16x16x128_f8f6f4 v[136:139], v[24:31], v[194:201], v[136:139], v186, v187 op_sel_hi:[0,0,0]
	v_mfma_scale_f32_16x16x128_f8f6f4 v[124:127], v[16:23], v[202:209], v[124:127], v186, v187 op_sel_hi:[0,0,0]
	v_mfma_scale_f32_16x16x128_f8f6f4 v[120:123], v[24:31], v[202:209], v[120:123], v186, v187 op_sel_hi:[0,0,0]
	v_mfma_scale_f32_16x16x128_f8f6f4 v[108:111], v[16:23], v[210:217], v[108:111], v186, v187 op_sel_hi:[0,0,0]
	v_mfma_scale_f32_16x16x128_f8f6f4 v[104:107], v[24:31], v[210:217], v[104:107], v186, v187 op_sel_hi:[0,0,0]
	s_setprio 0
	s_setprio 1
	v_mfma_scale_f32_16x16x128_f8f6f4 v[148:151], v[0:7], v[176:183], v[148:151], v186, v187 op_sel_hi:[0,0,0]
	v_mfma_scale_f32_16x16x128_f8f6f4 v[144:147], v[8:15], v[176:183], v[144:147], v186, v187 op_sel_hi:[0,0,0]
	v_mfma_scale_f32_16x16x128_f8f6f4 v[132:135], v[0:7], v[194:201], v[132:135], v186, v187 op_sel_hi:[0,0,0]
	v_mfma_scale_f32_16x16x128_f8f6f4 v[128:131], v[8:15], v[194:201], v[128:131], v186, v187 op_sel_hi:[0,0,0]
	v_mfma_scale_f32_16x16x128_f8f6f4 v[116:119], v[0:7], v[202:209], v[116:119], v186, v187 op_sel_hi:[0,0,0]
	v_mfma_scale_f32_16x16x128_f8f6f4 v[112:115], v[8:15], v[202:209], v[112:115], v186, v187 op_sel_hi:[0,0,0]
	v_mfma_scale_f32_16x16x128_f8f6f4 v[100:103], v[0:7], v[210:217], v[100:103], v186, v187 op_sel_hi:[0,0,0]
	v_mfma_scale_f32_16x16x128_f8f6f4 v[96:99], v[8:15], v[210:217], v[96:99], v186, v187 op_sel_hi:[0,0,0]
	s_setprio 0
	s_barrier
	s_add_i32 s73, s67, s17
	v_lshl_add_u64 v[176:177], s[58:59], 0, v[162:163]
	s_mov_b32 m0, s73
	ds_read_b128 v[194:197], v193 offset:16384
	ds_read_b128 v[198:201], v193 offset:17408
	ds_read_b128 v[202:205], v193 offset:18432
	ds_read_b128 v[206:209], v193 offset:19456
	ds_read_b128 v[210:213], v193 offset:20480
	ds_read_b128 v[214:217], v193 offset:21504
	ds_read_b128 v[218:221], v193 offset:22528
	ds_read_b128 v[222:225], v193 offset:23552
	global_load_lds_dwordx4 v[176:177], off
	s_add_i32 m0, s73, 0x2000
	s_add_u32 s74, s58, 0x40000
	v_lshl_add_u64 v[178:179], s[58:59], 0, v[166:167]
	s_addc_u32 s75, s59, 0
	s_add_i32 s73, s68, s17
	global_load_lds_dwordx4 v[178:179], off
	v_lshl_add_u64 v[180:181], s[74:75], 0, v[162:163]
	s_mov_b32 m0, s73
	v_lshl_add_u64 v[182:183], s[60:61], 0, v[164:165]
	global_load_lds_dwordx4 v[180:181], off
	v_lshl_add_u64 v[180:181], s[74:75], 0, v[166:167]
	s_add_i32 m0, s73, 0x2000
	s_nop 0
	global_load_lds_dwordx4 v[180:181], off
	v_lshl_add_u64 v[180:181], s[60:61], 0, v[160:161]
	s_mov_b32 m0, s18
	s_nop 0
	global_load_lds_dwordx4 v[180:181], off
	s_mov_b32 m0, s19
	s_nop 0
	global_load_lds_dwordx4 v[182:183], off
	s_waitcnt vmcnt(9)
	s_waitcnt lgkmcnt(0)
	s_barrier
	s_setprio 1
	s_waitcnt lgkmcnt(0)
	v_mfma_scale_f32_16x16x128_f8f6f4 v[92:95], v[16:23], v[194:201], v[92:95], v186, v187 op_sel_hi:[0,0,0]
	v_mfma_scale_f32_16x16x128_f8f6f4 v[88:91], v[24:31], v[194:201], v[88:91], v186, v187 op_sel_hi:[0,0,0]
	v_mfma_scale_f32_16x16x128_f8f6f4 v[76:79], v[16:23], v[202:209], v[76:79], v186, v187 op_sel_hi:[0,0,0]
	v_mfma_scale_f32_16x16x128_f8f6f4 v[72:75], v[24:31], v[202:209], v[72:75], v186, v187 op_sel_hi:[0,0,0]
	v_mfma_scale_f32_16x16x128_f8f6f4 v[60:63], v[16:23], v[210:217], v[60:63], v186, v187 op_sel_hi:[0,0,0]
	v_mfma_scale_f32_16x16x128_f8f6f4 v[56:59], v[24:31], v[210:217], v[56:59], v186, v187 op_sel_hi:[0,0,0]
	v_mfma_scale_f32_16x16x128_f8f6f4 v[44:47], v[16:23], v[218:225], v[44:47], v186, v187 op_sel_hi:[0,0,0]
	v_mfma_scale_f32_16x16x128_f8f6f4 v[40:43], v[24:31], v[218:225], v[40:43], v186, v187 op_sel_hi:[0,0,0]
	s_setprio 0
	s_setprio 1
	v_mfma_scale_f32_16x16x128_f8f6f4 v[84:87], v[0:7], v[194:201], v[84:87], v186, v187 op_sel_hi:[0,0,0]
	v_mfma_scale_f32_16x16x128_f8f6f4 v[80:83], v[8:15], v[194:201], v[80:83], v186, v187 op_sel_hi:[0,0,0]
	v_mfma_scale_f32_16x16x128_f8f6f4 v[68:71], v[0:7], v[202:209], v[68:71], v186, v187 op_sel_hi:[0,0,0]
	v_mfma_scale_f32_16x16x128_f8f6f4 v[64:67], v[8:15], v[202:209], v[64:67], v186, v187 op_sel_hi:[0,0,0]
	v_mfma_scale_f32_16x16x128_f8f6f4 v[52:55], v[0:7], v[210:217], v[52:55], v186, v187 op_sel_hi:[0,0,0]
	v_mfma_scale_f32_16x16x128_f8f6f4 v[48:51], v[8:15], v[210:217], v[48:51], v186, v187 op_sel_hi:[0,0,0]
	v_mfma_scale_f32_16x16x128_f8f6f4 v[36:39], v[0:7], v[218:225], v[36:39], v186, v187 op_sel_hi:[0,0,0]
	v_mfma_scale_f32_16x16x128_f8f6f4 v[32:35], v[8:15], v[218:225], v[32:35], v186, v187 op_sel_hi:[0,0,0]
	s_setprio 0
	s_barrier
	s_add_i32 s73, 0, 0x18000
	s_add_i32 s74, 0, 0x1c000
	v_add_u32_e32 v12, s73, v189
	v_add_u32_e32 v28, s74, v189
	ds_read_b128 v[0:3], v12
	ds_read_b128 v[4:7], v12 offset:1024
	ds_read_b128 v[8:11], v12 offset:2048
	ds_read_b128 v[12:15], v12 offset:3072
	ds_read_b128 v[16:19], v28
	ds_read_b128 v[20:23], v28 offset:1024
	ds_read_b128 v[24:27], v28 offset:2048
	ds_read_b128 v[28:31], v28 offset:3072
	s_add_u32 s60, s60, 0x40000
	s_addc_u32 s61, s61, 0
	s_mov_b32 m0, s26
	v_lshl_add_u64 v[226:227], s[60:61], 0, v[160:161]
	ds_read_b128 v[194:197], v193 offset:32768
	ds_read_b128 v[198:201], v193 offset:33792
	ds_read_b128 v[202:205], v193 offset:34816
	ds_read_b128 v[206:209], v193 offset:35840
	ds_read_b128 v[210:213], v193 offset:36864
	ds_read_b128 v[214:217], v193 offset:37888
	ds_read_b128 v[218:221], v193 offset:38912
	ds_read_b128 v[222:225], v193 offset:39936
	global_load_lds_dwordx4 v[226:227], off
	v_lshl_add_u64 v[226:227], s[60:61], 0, v[164:165]
	s_mov_b32 m0, s27
	s_nop 0
	global_load_lds_dwordx4 v[226:227], off
	s_waitcnt vmcnt(9)
	s_waitcnt lgkmcnt(0)
	s_barrier
	s_setprio 1
	s_waitcnt lgkmcnt(0)
	v_mfma_scale_f32_16x16x128_f8f6f4 v[156:159], v[0:7], v[194:201], v[156:159], v186, v187 op_sel_hi:[0,0,0]
	v_mfma_scale_f32_16x16x128_f8f6f4 v[152:155], v[8:15], v[194:201], v[152:155], v186, v187 op_sel_hi:[0,0,0]
	v_mfma_scale_f32_16x16x128_f8f6f4 v[140:143], v[0:7], v[202:209], v[140:143], v186, v187 op_sel_hi:[0,0,0]
	v_mfma_scale_f32_16x16x128_f8f6f4 v[136:139], v[8:15], v[202:209], v[136:139], v186, v187 op_sel_hi:[0,0,0]
	v_mfma_scale_f32_16x16x128_f8f6f4 v[124:127], v[0:7], v[210:217], v[124:127], v186, v187 op_sel_hi:[0,0,0]
	v_mfma_scale_f32_16x16x128_f8f6f4 v[120:123], v[8:15], v[210:217], v[120:123], v186, v187 op_sel_hi:[0,0,0]
	v_mfma_scale_f32_16x16x128_f8f6f4 v[108:111], v[0:7], v[218:225], v[108:111], v186, v187 op_sel_hi:[0,0,0]
	v_mfma_scale_f32_16x16x128_f8f6f4 v[104:107], v[8:15], v[218:225], v[104:107], v186, v187 op_sel_hi:[0,0,0]
	s_setprio 0
	s_setprio 1
	v_mfma_scale_f32_16x16x128_f8f6f4 v[148:151], v[16:23], v[194:201], v[148:151], v186, v187 op_sel_hi:[0,0,0]
	v_mfma_scale_f32_16x16x128_f8f6f4 v[144:147], v[24:31], v[194:201], v[144:147], v186, v187 op_sel_hi:[0,0,0]
	v_mfma_scale_f32_16x16x128_f8f6f4 v[132:135], v[16:23], v[202:209], v[132:135], v186, v187 op_sel_hi:[0,0,0]
	v_mfma_scale_f32_16x16x128_f8f6f4 v[128:131], v[24:31], v[202:209], v[128:131], v186, v187 op_sel_hi:[0,0,0]
	v_mfma_scale_f32_16x16x128_f8f6f4 v[116:119], v[16:23], v[210:217], v[116:119], v186, v187 op_sel_hi:[0,0,0]
	v_mfma_scale_f32_16x16x128_f8f6f4 v[112:115], v[24:31], v[210:217], v[112:115], v186, v187 op_sel_hi:[0,0,0]
	v_mfma_scale_f32_16x16x128_f8f6f4 v[100:103], v[16:23], v[218:225], v[100:103], v186, v187 op_sel_hi:[0,0,0]
	v_mfma_scale_f32_16x16x128_f8f6f4 v[96:99], v[24:31], v[218:225], v[96:99], v186, v187 op_sel_hi:[0,0,0]
	s_setprio 0
	s_barrier
	s_add_i32 s60, s73, s17
	v_lshl_add_u64 v[176:177], v[176:177], 0, s[10:11]
	s_mov_b32 m0, s60
	ds_read_b128 v[194:197], v193 offset:49152
	ds_read_b128 v[198:201], v193 offset:50176
	ds_read_b128 v[202:205], v193 offset:51200
	ds_read_b128 v[206:209], v193 offset:52224
	ds_read_b128 v[210:213], v193 offset:53248
	ds_read_b128 v[214:217], v193 offset:54272
	ds_read_b128 v[218:221], v193 offset:55296
	ds_read_b128 v[222:225], v193 offset:56320
	global_load_lds_dwordx4 v[176:177], off
	s_add_i32 m0, s60, 0x2000
	s_add_u32 s58, s58, 0x40080
	v_lshl_add_u64 v[176:177], v[178:179], 0, s[10:11]
	s_addc_u32 s59, s59, 0
	s_add_i32 s60, s74, s17
	global_load_lds_dwordx4 v[176:177], off
	v_lshl_add_u64 v[176:177], s[58:59], 0, v[162:163]
	s_mov_b32 m0, s60
	s_nop 0
	global_load_lds_dwordx4 v[176:177], off
	v_lshl_add_u64 v[176:177], s[58:59], 0, v[166:167]
	s_add_i32 m0, s60, 0x2000
	s_nop 0
	global_load_lds_dwordx4 v[176:177], off
	v_lshl_add_u64 v[176:177], v[180:181], 0, s[10:11]
	s_mov_b32 m0, s35
	s_nop 0
	global_load_lds_dwordx4 v[176:177], off
	v_lshl_add_u64 v[176:177], v[182:183], 0, s[10:11]
	s_mov_b32 m0, s55
	s_nop 0
	global_load_lds_dwordx4 v[176:177], off
	s_waitcnt vmcnt(8)
	s_waitcnt lgkmcnt(0)
	s_barrier
	s_setprio 1
	s_waitcnt lgkmcnt(0)
	v_mfma_scale_f32_16x16x128_f8f6f4 v[92:95], v[0:7], v[194:201], v[92:95], v186, v187 op_sel_hi:[0,0,0]
	v_mfma_scale_f32_16x16x128_f8f6f4 v[88:91], v[8:15], v[194:201], v[88:91], v186, v187 op_sel_hi:[0,0,0]
	v_mfma_scale_f32_16x16x128_f8f6f4 v[76:79], v[0:7], v[202:209], v[76:79], v186, v187 op_sel_hi:[0,0,0]
	v_mfma_scale_f32_16x16x128_f8f6f4 v[72:75], v[8:15], v[202:209], v[72:75], v186, v187 op_sel_hi:[0,0,0]
	v_mfma_scale_f32_16x16x128_f8f6f4 v[60:63], v[0:7], v[210:217], v[60:63], v186, v187 op_sel_hi:[0,0,0]
	v_mfma_scale_f32_16x16x128_f8f6f4 v[56:59], v[8:15], v[210:217], v[56:59], v186, v187 op_sel_hi:[0,0,0]
	v_mfma_scale_f32_16x16x128_f8f6f4 v[44:47], v[0:7], v[218:225], v[44:47], v186, v187 op_sel_hi:[0,0,0]
	v_mfma_scale_f32_16x16x128_f8f6f4 v[40:43], v[8:15], v[218:225], v[40:43], v186, v187 op_sel_hi:[0,0,0]
	s_setprio 0
	s_setprio 1
	v_mfma_scale_f32_16x16x128_f8f6f4 v[84:87], v[16:23], v[194:201], v[84:87], v186, v187 op_sel_hi:[0,0,0]
	v_mfma_scale_f32_16x16x128_f8f6f4 v[80:83], v[24:31], v[194:201], v[80:83], v186, v187 op_sel_hi:[0,0,0]
	v_mfma_scale_f32_16x16x128_f8f6f4 v[68:71], v[16:23], v[202:209], v[68:71], v186, v187 op_sel_hi:[0,0,0]
	v_mfma_scale_f32_16x16x128_f8f6f4 v[64:67], v[24:31], v[202:209], v[64:67], v186, v187 op_sel_hi:[0,0,0]
	v_mfma_scale_f32_16x16x128_f8f6f4 v[52:55], v[16:23], v[210:217], v[52:55], v186, v187 op_sel_hi:[0,0,0]
	v_mfma_scale_f32_16x16x128_f8f6f4 v[48:51], v[24:31], v[210:217], v[48:51], v186, v187 op_sel_hi:[0,0,0]
	v_mfma_scale_f32_16x16x128_f8f6f4 v[36:39], v[16:23], v[218:225], v[36:39], v186, v187 op_sel_hi:[0,0,0]
	v_mfma_scale_f32_16x16x128_f8f6f4 v[32:35], v[24:31], v[218:225], v[32:35], v186, v187 op_sel_hi:[0,0,0]
	s_setprio 0
	s_barrier
	s_add_i32 s72, s72, 2
	s_add_u32 s56, s56, 0x100
	s_addc_u32 s57, s57, 0
	s_add_u32 s70, s70, 0x100
	s_addc_u32 s71, s71, 0
	s_cmp_gt_u32 s72, 13
	s_cbranch_scc0 .LBB0_872
	s_and_b64 vcc, exec, s[12:13]
	s_cbranch_vccz .LBB0_875
	s_barrier

.LBB0_1195:
	ds_read_b128 v[16:19], v191
	ds_read_b128 v[20:23], v191 offset:1024
	ds_read_b128 v[24:27], v191 offset:2048
	ds_read_b128 v[28:31], v191 offset:3072
	ds_read_b128 v[0:3], v192
	ds_read_b128 v[4:7], v192 offset:1024
	ds_read_b128 v[8:11], v192 offset:2048
	ds_read_b128 v[12:15], v192 offset:3072
	s_add_u32 s52, s48, 0xfff00080
	s_addc_u32 s53, s49, -1
	s_cmp_eq_u32 s66, 60
	s_cselect_b32 s55, s39, s53
	s_cselect_b32 s54, s45, s52
	s_cselect_b32 s53, s37, s65
	s_cselect_b32 s52, s63, s64
	v_lshl_add_u64 v[218:219], s[48:49], 0, v[168:169]
	s_add_i32 m0, s26, 0xc000
	ds_read_b128 v[176:179], v193
	ds_read_b128 v[180:183], v193 offset:1024
	ds_read_b128 v[194:197], v193 offset:2048
	ds_read_b128 v[198:201], v193 offset:3072
	ds_read_b128 v[202:205], v193 offset:4096
	ds_read_b128 v[206:209], v193 offset:5120
	ds_read_b128 v[210:213], v193 offset:6144
	ds_read_b128 v[214:217], v193 offset:7168
	global_load_lds_dwordx4 v[218:219], off
	v_lshl_add_u64 v[218:219], s[48:49], 0, v[170:171]
	s_add_i32 m0, s26, 0xe000
	s_nop 0
	global_load_lds_dwordx4 v[218:219], off
	s_waitcnt vmcnt(8)
	s_add_u32 s79, s66, 2
	s_lshr_b32 s86, s79, 4
	s_lshl_b32 s86, s86, 23
	s_and_b32 s87, s79, 15
	s_lshl_b32 s87, s87, 8
	s_add_u32 s86, s86, s87
	v_add_u32_e32 v229, s86, v228
	global_load_dword v230, v229, s[80:81] sc1
	s_nop 0
	s_waitcnt lgkmcnt(0)
	s_barrier
	s_setprio 1
	s_waitcnt lgkmcnt(0)
	v_mfma_scale_f32_16x16x128_f8f6f4 v[156:159], v[16:23], v[176:183], v[156:159], v186, v187 op_sel_hi:[0,0,0]
	v_mfma_scale_f32_16x16x128_f8f6f4 v[152:155], v[24:31], v[176:183], v[152:155], v186, v187 op_sel_hi:[0,0,0]
	v_mfma_scale_f32_16x16x128_f8f6f4 v[140:143], v[16:23], v[194:201], v[140:143], v186, v187 op_sel_hi:[0,0,0]
	v_mfma_scale_f32_16x16x128_f8f6f4 v[136:139], v[24:31], v[194:201], v[136:139], v186, v187 op_sel_hi:[0,0,0]
	v_mfma_scale_f32_16x16x128_f8f6f4 v[124:127], v[16:23], v[202:209], v[124:127], v186, v187 op_sel_hi:[0,0,0]
	v_mfma_scale_f32_16x16x128_f8f6f4 v[120:123], v[24:31], v[202:209], v[120:123], v186, v187 op_sel_hi:[0,0,0]
	v_mfma_scale_f32_16x16x128_f8f6f4 v[108:111], v[16:23], v[210:217], v[108:111], v186, v187 op_sel_hi:[0,0,0]
	v_mfma_scale_f32_16x16x128_f8f6f4 v[104:107], v[24:31], v[210:217], v[104:107], v186, v187 op_sel_hi:[0,0,0]
	s_setprio 0
	s_setprio 1
	v_mfma_scale_f32_16x16x128_f8f6f4 v[148:151], v[0:7], v[176:183], v[148:151], v186, v187 op_sel_hi:[0,0,0]
	v_mfma_scale_f32_16x16x128_f8f6f4 v[144:147], v[8:15], v[176:183], v[144:147], v186, v187 op_sel_hi:[0,0,0]
	v_mfma_scale_f32_16x16x128_f8f6f4 v[132:135], v[0:7], v[194:201], v[132:135], v186, v187 op_sel_hi:[0,0,0]
	v_mfma_scale_f32_16x16x128_f8f6f4 v[128:131], v[8:15], v[194:201], v[128:131], v186, v187 op_sel_hi:[0,0,0]
	v_mfma_scale_f32_16x16x128_f8f6f4 v[116:119], v[0:7], v[202:209], v[116:119], v186, v187 op_sel_hi:[0,0,0]
	v_mfma_scale_f32_16x16x128_f8f6f4 v[112:115], v[8:15], v[202:209], v[112:115], v186, v187 op_sel_hi:[0,0,0]
	v_mfma_scale_f32_16x16x128_f8f6f4 v[100:103], v[0:7], v[210:217], v[100:103], v186, v187 op_sel_hi:[0,0,0]
	v_mfma_scale_f32_16x16x128_f8f6f4 v[96:99], v[8:15], v[210:217], v[96:99], v186, v187 op_sel_hi:[0,0,0]
	s_setprio 0
	s_barrier
	s_add_i32 s67, s61, s17
	v_lshl_add_u64 v[176:177], s[52:53], 0, v[162:163]
	s_mov_b32 m0, s67
	ds_read_b128 v[194:197], v193 offset:16384
	ds_read_b128 v[198:201], v193 offset:17408
	ds_read_b128 v[202:205], v193 offset:18432
	ds_read_b128 v[206:209], v193 offset:19456
	ds_read_b128 v[210:213], v193 offset:20480
	ds_read_b128 v[214:217], v193 offset:21504
	ds_read_b128 v[218:221], v193 offset:22528
	ds_read_b128 v[222:225], v193 offset:23552
	global_load_lds_dwordx4 v[176:177], off
	s_add_i32 m0, s67, 0x2000
	s_add_u32 s68, s52, 0x100000
	v_lshl_add_u64 v[178:179], s[52:53], 0, v[166:167]
	s_addc_u32 s69, s53, 0
	s_add_i32 s67, s62, s17
	global_load_lds_dwordx4 v[178:179], off
	v_lshl_add_u64 v[180:181], s[68:69], 0, v[162:163]
	s_mov_b32 m0, s67
	v_lshl_add_u64 v[182:183], s[54:55], 0, v[164:165]
	global_load_lds_dwordx4 v[180:181], off
	v_lshl_add_u64 v[180:181], s[68:69], 0, v[166:167]
	s_add_i32 m0, s67, 0x2000
	s_nop 0
	global_load_lds_dwordx4 v[180:181], off
	v_lshl_add_u64 v[180:181], s[54:55], 0, v[160:161]
	s_mov_b32 m0, s26
	s_nop 0
	global_load_lds_dwordx4 v[180:181], off
	s_mov_b32 m0, s27
	s_nop 0
	global_load_lds_dwordx4 v[182:183], off
	s_waitcnt vmcnt(9)
	s_waitcnt lgkmcnt(0)
	s_barrier
	s_setprio 1
	s_waitcnt lgkmcnt(0)
	v_mfma_scale_f32_16x16x128_f8f6f4 v[92:95], v[16:23], v[194:201], v[92:95], v186, v187 op_sel_hi:[0,0,0]
	v_mfma_scale_f32_16x16x128_f8f6f4 v[88:91], v[24:31], v[194:201], v[88:91], v186, v187 op_sel_hi:[0,0,0]
	v_mfma_scale_f32_16x16x128_f8f6f4 v[76:79], v[16:23], v[202:209], v[76:79], v186, v187 op_sel_hi:[0,0,0]
	v_mfma_scale_f32_16x16x128_f8f6f4 v[72:75], v[24:31], v[202:209], v[72:75], v186, v187 op_sel_hi:[0,0,0]
	v_mfma_scale_f32_16x16x128_f8f6f4 v[60:63], v[16:23], v[210:217], v[60:63], v186, v187 op_sel_hi:[0,0,0]
	v_mfma_scale_f32_16x16x128_f8f6f4 v[56:59], v[24:31], v[210:217], v[56:59], v186, v187 op_sel_hi:[0,0,0]
	v_mfma_scale_f32_16x16x128_f8f6f4 v[44:47], v[16:23], v[218:225], v[44:47], v186, v187 op_sel_hi:[0,0,0]
	v_mfma_scale_f32_16x16x128_f8f6f4 v[40:43], v[24:31], v[218:225], v[40:43], v186, v187 op_sel_hi:[0,0,0]
	s_setprio 0
	s_setprio 1
	v_mfma_scale_f32_16x16x128_f8f6f4 v[84:87], v[0:7], v[194:201], v[84:87], v186, v187 op_sel_hi:[0,0,0]
	v_mfma_scale_f32_16x16x128_f8f6f4 v[80:83], v[8:15], v[194:201], v[80:83], v186, v187 op_sel_hi:[0,0,0]
	v_mfma_scale_f32_16x16x128_f8f6f4 v[68:71], v[0:7], v[202:209], v[68:71], v186, v187 op_sel_hi:[0,0,0]
	v_mfma_scale_f32_16x16x128_f8f6f4 v[64:67], v[8:15], v[202:209], v[64:67], v186, v187 op_sel_hi:[0,0,0]
	v_mfma_scale_f32_16x16x128_f8f6f4 v[52:55], v[0:7], v[210:217], v[52:55], v186, v187 op_sel_hi:[0,0,0]
	v_mfma_scale_f32_16x16x128_f8f6f4 v[48:51], v[8:15], v[210:217], v[48:51], v186, v187 op_sel_hi:[0,0,0]
	v_mfma_scale_f32_16x16x128_f8f6f4 v[36:39], v[0:7], v[218:225], v[36:39], v186, v187 op_sel_hi:[0,0,0]
	v_mfma_scale_f32_16x16x128_f8f6f4 v[32:35], v[8:15], v[218:225], v[32:35], v186, v187 op_sel_hi:[0,0,0]
	s_setprio 0
	s_barrier
	s_add_i32 s67, 0, 0x18000
	s_add_i32 s68, 0, 0x1c000
	v_add_u32_e32 v12, s67, v189
	v_add_u32_e32 v28, s68, v189
	ds_read_b128 v[0:3], v12
	ds_read_b128 v[4:7], v12 offset:1024
	ds_read_b128 v[8:11], v12 offset:2048
	ds_read_b128 v[12:15], v12 offset:3072
	ds_read_b128 v[16:19], v28
	ds_read_b128 v[20:23], v28 offset:1024
	ds_read_b128 v[24:27], v28 offset:2048
	ds_read_b128 v[28:31], v28 offset:3072
	s_add_u32 s54, s54, 0x100000
	s_addc_u32 s55, s55, 0
	s_mov_b32 m0, s33
	v_lshl_add_u64 v[226:227], s[54:55], 0, v[160:161]
	ds_read_b128 v[194:197], v193 offset:32768
	ds_read_b128 v[198:201], v193 offset:33792
	ds_read_b128 v[202:205], v193 offset:34816
	ds_read_b128 v[206:209], v193 offset:35840
	ds_read_b128 v[210:213], v193 offset:36864
	ds_read_b128 v[214:217], v193 offset:37888
	ds_read_b128 v[218:221], v193 offset:38912
	ds_read_b128 v[222:225], v193 offset:39936
	global_load_lds_dwordx4 v[226:227], off
	v_lshl_add_u64 v[226:227], s[54:55], 0, v[164:165]
	s_mov_b32 m0, s35
	s_nop 0
	global_load_lds_dwordx4 v[226:227], off
	s_waitcnt vmcnt(9)
	s_waitcnt lgkmcnt(0)
	s_barrier
	s_setprio 1
	s_waitcnt lgkmcnt(0)
	v_mfma_scale_f32_16x16x128_f8f6f4 v[156:159], v[0:7], v[194:201], v[156:159], v186, v187 op_sel_hi:[0,0,0]
	v_mfma_scale_f32_16x16x128_f8f6f4 v[152:155], v[8:15], v[194:201], v[152:155], v186, v187 op_sel_hi:[0,0,0]
	v_mfma_scale_f32_16x16x128_f8f6f4 v[140:143], v[0:7], v[202:209], v[140:143], v186, v187 op_sel_hi:[0,0,0]
	v_mfma_scale_f32_16x16x128_f8f6f4 v[136:139], v[8:15], v[202:209], v[136:139], v186, v187 op_sel_hi:[0,0,0]
	v_mfma_scale_f32_16x16x128_f8f6f4 v[124:127], v[0:7], v[210:217], v[124:127], v186, v187 op_sel_hi:[0,0,0]
	v_mfma_scale_f32_16x16x128_f8f6f4 v[120:123], v[8:15], v[210:217], v[120:123], v186, v187 op_sel_hi:[0,0,0]
	v_mfma_scale_f32_16x16x128_f8f6f4 v[108:111], v[0:7], v[218:225], v[108:111], v186, v187 op_sel_hi:[0,0,0]
	v_mfma_scale_f32_16x16x128_f8f6f4 v[104:107], v[8:15], v[218:225], v[104:107], v186, v187 op_sel_hi:[0,0,0]
	s_setprio 0
	s_setprio 1
	v_mfma_scale_f32_16x16x128_f8f6f4 v[148:151], v[16:23], v[194:201], v[148:151], v186, v187 op_sel_hi:[0,0,0]
	v_mfma_scale_f32_16x16x128_f8f6f4 v[144:147], v[24:31], v[194:201], v[144:147], v186, v187 op_sel_hi:[0,0,0]
	v_mfma_scale_f32_16x16x128_f8f6f4 v[132:135], v[16:23], v[202:209], v[132:135], v186, v187 op_sel_hi:[0,0,0]
	v_mfma_scale_f32_16x16x128_f8f6f4 v[128:131], v[24:31], v[202:209], v[128:131], v186, v187 op_sel_hi:[0,0,0]
	v_mfma_scale_f32_16x16x128_f8f6f4 v[116:119], v[16:23], v[210:217], v[116:119], v186, v187 op_sel_hi:[0,0,0]
	v_mfma_scale_f32_16x16x128_f8f6f4 v[112:115], v[24:31], v[210:217], v[112:115], v186, v187 op_sel_hi:[0,0,0]
	v_mfma_scale_f32_16x16x128_f8f6f4 v[100:103], v[16:23], v[218:225], v[100:103], v186, v187 op_sel_hi:[0,0,0]
	v_mfma_scale_f32_16x16x128_f8f6f4 v[96:99], v[24:31], v[218:225], v[96:99], v186, v187 op_sel_hi:[0,0,0]
	s_setprio 0
	s_barrier
	s_add_i32 s54, s67, s17
	v_lshl_add_u64 v[176:177], v[176:177], 0, s[10:11]
	s_mov_b32 m0, s54
	ds_read_b128 v[194:197], v193 offset:49152
	ds_read_b128 v[198:201], v193 offset:50176
	ds_read_b128 v[202:205], v193 offset:51200
	ds_read_b128 v[206:209], v193 offset:52224
	ds_read_b128 v[210:213], v193 offset:53248
	ds_read_b128 v[214:217], v193 offset:54272
	ds_read_b128 v[218:221], v193 offset:55296
	ds_read_b128 v[222:225], v193 offset:56320
	global_load_lds_dwordx4 v[176:177], off
	s_add_i32 m0, s54, 0x2000
	s_add_u32 s52, s52, 0x100080
	v_lshl_add_u64 v[176:177], v[178:179], 0, s[10:11]
	s_addc_u32 s53, s53, 0
	s_add_i32 s54, s68, s17
	global_load_lds_dwordx4 v[176:177], off
	v_lshl_add_u64 v[176:177], s[52:53], 0, v[162:163]
	s_mov_b32 m0, s54
	s_nop 0
	global_load_lds_dwordx4 v[176:177], off
	v_lshl_add_u64 v[176:177], s[52:53], 0, v[166:167]
	s_add_i32 m0, s54, 0x2000
	s_nop 0
	global_load_lds_dwordx4 v[176:177], off
	v_lshl_add_u64 v[176:177], v[180:181], 0, s[10:11]
	s_mov_b32 m0, s56
	s_nop 0
	global_load_lds_dwordx4 v[176:177], off
	v_lshl_add_u64 v[176:177], v[182:183], 0, s[10:11]
	s_mov_b32 m0, s57
	s_nop 0
	global_load_lds_dwordx4 v[176:177], off
	s_waitcnt vmcnt(8)
	s_waitcnt lgkmcnt(0)
	s_barrier
	s_setprio 1
	s_waitcnt lgkmcnt(0)
	v_mfma_scale_f32_16x16x128_f8f6f4 v[92:95], v[0:7], v[194:201], v[92:95], v186, v187 op_sel_hi:[0,0,0]
	v_mfma_scale_f32_16x16x128_f8f6f4 v[88:91], v[8:15], v[194:201], v[88:91], v186, v187 op_sel_hi:[0,0,0]
	v_mfma_scale_f32_16x16x128_f8f6f4 v[76:79], v[0:7], v[202:209], v[76:79], v186, v187 op_sel_hi:[0,0,0]
	v_mfma_scale_f32_16x16x128_f8f6f4 v[72:75], v[8:15], v[202:209], v[72:75], v186, v187 op_sel_hi:[0,0,0]
	v_mfma_scale_f32_16x16x128_f8f6f4 v[60:63], v[0:7], v[210:217], v[60:63], v186, v187 op_sel_hi:[0,0,0]
	v_mfma_scale_f32_16x16x128_f8f6f4 v[56:59], v[8:15], v[210:217], v[56:59], v186, v187 op_sel_hi:[0,0,0]
	v_mfma_scale_f32_16x16x128_f8f6f4 v[44:47], v[0:7], v[218:225], v[44:47], v186, v187 op_sel_hi:[0,0,0]
	v_mfma_scale_f32_16x16x128_f8f6f4 v[40:43], v[8:15], v[218:225], v[40:43], v186, v187 op_sel_hi:[0,0,0]
	s_setprio 0
	s_setprio 1
	v_mfma_scale_f32_16x16x128_f8f6f4 v[84:87], v[16:23], v[194:201], v[84:87], v186, v187 op_sel_hi:[0,0,0]
	v_mfma_scale_f32_16x16x128_f8f6f4 v[80:83], v[24:31], v[194:201], v[80:83], v186, v187 op_sel_hi:[0,0,0]
	v_mfma_scale_f32_16x16x128_f8f6f4 v[68:71], v[16:23], v[202:209], v[68:71], v186, v187 op_sel_hi:[0,0,0]
	v_mfma_scale_f32_16x16x128_f8f6f4 v[64:67], v[24:31], v[202:209], v[64:67], v186, v187 op_sel_hi:[0,0,0]
	v_mfma_scale_f32_16x16x128_f8f6f4 v[52:55], v[16:23], v[210:217], v[52:55], v186, v187 op_sel_hi:[0,0,0]
	v_mfma_scale_f32_16x16x128_f8f6f4 v[48:51], v[24:31], v[210:217], v[48:51], v186, v187 op_sel_hi:[0,0,0]
	v_mfma_scale_f32_16x16x128_f8f6f4 v[36:39], v[16:23], v[218:225], v[36:39], v186, v187 op_sel_hi:[0,0,0]
	v_mfma_scale_f32_16x16x128_f8f6f4 v[32:35], v[24:31], v[218:225], v[32:35], v186, v187 op_sel_hi:[0,0,0]
	s_setprio 0
	s_barrier
	s_add_i32 s66, s66, 2
	s_add_u32 s48, s48, 0x100
	s_addc_u32 s49, s49, 0
	s_add_u32 s64, s64, 0x100
	s_addc_u32 s65, s65, 0
	s_cmp_gt_u32 s66, 61
	s_cbranch_scc0 .LBB0_1195
	s_and_b64 vcc, exec, s[12:13]
	s_cbranch_vccz .LBB0_1198
	s_barrier
